# mlstm m3 rmsnorm tail: 8 rows per wave interleaved (all LDS reads + gate loads issued up front, butterfly rounds batched across rows), on top of rotated attention loop
# speedup vs baseline: 1.0491x; 1.0220x over previous
.LBB0_448:
	s_or_b64 exec, exec, s[2:3]
	v_bfe_u32 v3, v1, 16, 1
	s_movk_i32 s2, 0x7fff
	v_lshlrev_b32_e32 v2, 3, v4
	v_add3_u32 v1, v1, v3, s2
	ds_write_b16_d16_hi v0, v1 offset:60336
	v_mul_u32_u24_e32 v0, 0x90, v9
	v_lshlrev_b32_e32 v1, 1, v2
	s_waitcnt lgkmcnt(0)
	s_barrier
	v_add3_u32 v12, 0, v0, v1
	ds_read_b128 v[14:17], v10 offset:59904
	ds_read_b128 v[0:3], v12 offset:36864
	ds_read_b128 v[18:21], v10 offset:59968
	ds_read_b128 v[4:7], v12 offset:36928
	s_waitcnt lgkmcnt(2)
	v_mfma_f32_16x16x32_bf16 v[0:3], v[14:17], v[0:3], 0
	s_lshl_b32 s2, s4, 2
	s_add_i32 s2, s2, 0
	s_add_i32 s2, s2, 0x19200
	s_waitcnt lgkmcnt(0)
	v_mfma_f32_16x16x32_bf16 v[24:27], v[18:21], v[4:7], v[0:3]
	ds_read_b128 v[28:31], v10
	s_nop 1
	ds_read_b128 v[0:3], v12 offset:57600
	ds_read_b128 v[32:35], v10 offset:64
	ds_read_b128 v[4:7], v12 offset:57664
	s_ashr_i32 s3, s40, 6
	s_waitcnt lgkmcnt(2)
	v_mfma_f32_16x16x32_bf16 v[0:3], v[28:31], v[0:3], 0
	v_readlane_b32 s7, v254, 34
	s_waitcnt lgkmcnt(0)
	v_mfma_f32_16x16x32_bf16 v[36:39], v[32:35], v[4:7], v[0:3]
	s_nop 4
	v_and_b32_e32 v0, 48, v23
	v_add_u32_e32 v4, s2, v0
	v_and_or_b32 v0, v201, 64, v0
	v_lshlrev_b32_e32 v12, 2, v0
	ds_read_b128 v[0:3], v4 offset:512
	ds_read_b128 v[4:7], v4 offset:768
	s_lshl_b32 s2, s3, 4
	s_and_b32 s6, s2, 0xffffffc0
	v_or_b32_e32 v40, s6, v9
	s_waitcnt lgkmcnt(1)
	v_fma_f32 v13, v36, v0, v24
	v_fma_f32 v23, v37, v1, v25
	v_fma_f32 v24, v38, v2, v26
	v_fmac_f32_e32 v27, v39, v3
	v_mad_u64_u32 v[36:37], s[4:5], v40, s84, v[8:9]
	ds_bpermute_b32 v38, v12, v24
	ds_bpermute_b32 v39, v12, v27
	ds_read_b128 v[24:27], v36 offset:18432
	s_waitcnt lgkmcnt(0)
	v_mfma_f32_16x16x32_bf16 v[14:17], v[14:17], v[24:27], 0
	ds_read_b128 v[24:27], v36 offset:18496
	ds_bpermute_b32 v13, v12, v13
	v_max_f32_e32 v4, v4, v4
	s_waitcnt lgkmcnt(1)
	v_mfma_f32_16x16x32_bf16 v[14:17], v[18:21], v[24:27], v[14:17]
	ds_read_b128 v[18:21], v36 offset:39168
	ds_read_b128 v[24:27], v36 offset:39232
	s_waitcnt lgkmcnt(2)
	v_max_f32_e64 v13, |v13|, |v13|
	s_waitcnt lgkmcnt(1)
	v_mfma_f32_16x16x32_bf16 v[18:21], v[28:31], v[18:21], 0
	v_max_f32_e32 v4, v13, v4
	ds_bpermute_b32 v23, v12, v23
	v_lshl_add_u32 v12, v9, 2, s7
	s_waitcnt lgkmcnt(1)
	v_mfma_f32_16x16x32_bf16 v[18:21], v[32:35], v[24:27], v[18:21]
	v_lshl_add_u32 v24, s6, 2, v12
	s_movk_i32 s6, 0x210
	v_mad_u32_u24 v36, v11, s6, v24
	v_max_f32_e32 v5, v5, v5
	v_max_f32_e32 v6, v6, v6
	s_nop 2
	v_fma_f32 v14, v0, v18, v14
	v_div_scale_f32 v13, s[4:5], v4, v4, v14
	v_rcp_f32_e32 v18, v13
	v_max_f32_e32 v7, v7, v7
	v_fmac_f32_e32 v17, v3, v21
	s_or_b32 s2, s2, 48
	v_fma_f32 v25, -v13, v18, 1.0
	v_fmac_f32_e32 v18, v25, v18
	v_div_scale_f32 v25, vcc, v14, v4, v14
	v_mul_f32_e32 v26, v25, v18
	v_fma_f32 v27, -v13, v26, v25
	v_fmac_f32_e32 v26, v27, v18
	v_fma_f32 v13, -v13, v26, v25
	v_div_fmas_f32 v13, v13, v18, v26
	v_div_fixup_f32 v13, v13, v4, v14
	s_waitcnt lgkmcnt(0)
	v_max_f32_e64 v14, |v23|, |v23|
	ds_write_b32 v36, v13
	v_fma_f32 v13, v1, v19, v15
	v_max_f32_e32 v5, v14, v5
	v_div_scale_f32 v14, s[4:5], v5, v5, v13
	v_rcp_f32_e32 v15, v14
	s_nop 0
	v_fma_f32 v18, -v14, v15, 1.0
	v_fmac_f32_e32 v15, v18, v15
	v_div_scale_f32 v18, vcc, v13, v5, v13
	v_mul_f32_e32 v19, v18, v15
	v_fma_f32 v23, -v14, v19, v18
	v_fmac_f32_e32 v19, v23, v15
	v_fma_f32 v14, -v14, v19, v18
	v_div_fmas_f32 v14, v14, v15, v19
	v_div_fixup_f32 v14, v14, v5, v13
	v_mad_u32_u24 v13, v11, s6, s6
	v_add_u32_e32 v23, v24, v13
	v_max_f32_e64 v15, |v38|, |v38|
	ds_write_b32 v23, v14
	v_fma_f32 v14, v2, v20, v16
	v_max_f32_e32 v6, v15, v6
	v_div_scale_f32 v15, s[4:5], v6, v6, v14
	v_rcp_f32_e32 v16, v15
	s_nop 0
	v_fma_f32 v18, -v15, v16, 1.0
	v_fmac_f32_e32 v16, v18, v16
	v_div_scale_f32 v18, vcc, v14, v6, v14
	v_mul_f32_e32 v19, v18, v16
	v_fma_f32 v20, -v15, v19, v18
	v_fmac_f32_e32 v19, v20, v16
	v_fma_f32 v15, -v15, v19, v18
	v_div_fmas_f32 v15, v15, v16, v19
	v_div_fixup_f32 v15, v15, v6, v14
	v_mov_b32_e32 v14, 0x420
	v_mad_u32_u24 v14, v11, s6, v14
	v_add_u32_e32 v37, v24, v14
	ds_write_b32 v37, v15
	v_max_f32_e64 v15, |v39|, |v39|
	v_max_f32_e32 v7, v15, v7
	v_div_scale_f32 v15, s[4:5], v7, v7, v17
	v_rcp_f32_e32 v16, v15
	s_nop 0
	v_fma_f32 v18, -v15, v16, 1.0
	v_fmac_f32_e32 v16, v18, v16
	v_div_scale_f32 v18, vcc, v17, v7, v17
	v_mul_f32_e32 v19, v18, v16
	v_fma_f32 v20, -v15, v19, v18
	v_fmac_f32_e32 v19, v20, v16
	v_fma_f32 v15, -v15, v19, v18
	v_div_fmas_f32 v15, v15, v16, v19
	v_div_fixup_f32 v16, v15, v7, v17
	v_mad_u32_u24 v15, v11, s6, v206
	v_add_u32_e32 v38, v24, v15
	ds_write_b32 v38, v16
	v_or_b32_e32 v16, 16, v40
	v_mad_u64_u32 v[20:21], s[4:5], v16, s84, v[8:9]
	ds_read_b128 v[16:19], v10 offset:59904
	ds_read_b128 v[24:27], v20 offset:18432
	s_waitcnt lgkmcnt(0)
	v_mfma_f32_16x16x32_bf16 v[16:19], v[16:19], v[24:27], 0
	ds_read_b128 v[24:27], v10 offset:59968
	ds_read_b128 v[28:31], v20 offset:18496
	s_waitcnt lgkmcnt(0)
	v_mfma_f32_16x16x32_bf16 v[16:19], v[24:27], v[28:31], v[16:19]
	ds_read_b128 v[24:27], v10
	ds_read_b128 v[28:31], v20 offset:39168
	s_waitcnt lgkmcnt(0)
	v_mfma_f32_16x16x32_bf16 v[24:27], v[24:27], v[28:31], 0
	ds_read_b128 v[28:31], v10 offset:64
	ds_read_b128 v[32:35], v20 offset:39232
	s_waitcnt lgkmcnt(0)
	v_mfma_f32_16x16x32_bf16 v[24:27], v[28:31], v[32:35], v[24:27]
	s_nop 7
	v_fma_f32 v16, v0, v24, v16
	v_div_scale_f32 v20, s[4:5], v4, v4, v16
	v_rcp_f32_e32 v21, v20
	v_fmac_f32_e32 v19, v3, v27
	v_fma_f32 v24, -v20, v21, 1.0
	v_fmac_f32_e32 v21, v24, v21
	v_div_scale_f32 v24, vcc, v16, v4, v16
	v_mul_f32_e32 v28, v24, v21
	v_fma_f32 v29, -v20, v28, v24
	v_fmac_f32_e32 v28, v29, v21
	v_fma_f32 v20, -v20, v28, v24
	v_div_fmas_f32 v20, v20, v21, v28
	v_div_fixup_f32 v16, v20, v4, v16
	ds_write_b32 v36, v16 offset:64
	v_fma_f32 v16, v1, v25, v17
	v_div_scale_f32 v17, s[4:5], v5, v5, v16
	v_rcp_f32_e32 v20, v17
	s_nop 0
	v_fma_f32 v21, -v17, v20, 1.0
	v_fmac_f32_e32 v20, v21, v20
	v_div_scale_f32 v21, vcc, v16, v5, v16
	v_mul_f32_e32 v24, v21, v20
	v_fma_f32 v25, -v17, v24, v21
	v_fmac_f32_e32 v24, v25, v20
	v_fma_f32 v17, -v17, v24, v21
	v_div_fmas_f32 v17, v17, v20, v24
	v_div_fixup_f32 v16, v17, v5, v16
	ds_write_b32 v23, v16 offset:64
	v_fma_f32 v16, v2, v26, v18
	v_div_scale_f32 v17, s[4:5], v6, v6, v16
	v_rcp_f32_e32 v18, v17
	s_nop 0
	v_fma_f32 v20, -v17, v18, 1.0
	v_fmac_f32_e32 v18, v20, v18
	v_div_scale_f32 v20, vcc, v16, v6, v16
	v_mul_f32_e32 v21, v20, v18
	v_fma_f32 v24, -v17, v21, v20
	v_fmac_f32_e32 v21, v24, v18
	v_fma_f32 v17, -v17, v21, v20
	v_div_fmas_f32 v17, v17, v18, v21
	v_div_fixup_f32 v16, v17, v6, v16
	ds_write_b32 v37, v16 offset:64
	v_div_scale_f32 v16, s[4:5], v7, v7, v19
	v_rcp_f32_e32 v17, v16
	s_nop 0
	v_fma_f32 v18, -v16, v17, 1.0
	v_fmac_f32_e32 v17, v18, v17
	v_div_scale_f32 v18, vcc, v19, v7, v19
	v_mul_f32_e32 v20, v18, v17
	v_fma_f32 v21, -v16, v20, v18
	v_fmac_f32_e32 v20, v21, v17
	v_fma_f32 v16, -v16, v20, v18
	v_div_fmas_f32 v16, v16, v17, v20
	v_div_fixup_f32 v16, v16, v7, v19
	ds_write_b32 v38, v16 offset:64
	v_or_b32_e32 v16, 32, v40
	v_mad_u64_u32 v[20:21], s[4:5], v16, s84, v[8:9]
	ds_read_b128 v[16:19], v10 offset:59904
	ds_read_b128 v[24:27], v20 offset:18432
	s_waitcnt lgkmcnt(0)
	v_mfma_f32_16x16x32_bf16 v[16:19], v[16:19], v[24:27], 0
	ds_read_b128 v[24:27], v10 offset:59968
	ds_read_b128 v[28:31], v20 offset:18496
	v_or_b32_e32 v9, s2, v9
	v_mad_u64_u32 v[8:9], s[4:5], v9, s84, v[8:9]
	s_waitcnt lgkmcnt(0)
	v_mfma_f32_16x16x32_bf16 v[16:19], v[24:27], v[28:31], v[16:19]
	ds_read_b128 v[24:27], v10
	ds_read_b128 v[28:31], v20 offset:39168
	s_waitcnt lgkmcnt(0)
	v_mfma_f32_16x16x32_bf16 v[24:27], v[24:27], v[28:31], 0
	ds_read_b128 v[28:31], v10 offset:64
	ds_read_b128 v[32:35], v20 offset:39232
	s_waitcnt lgkmcnt(0)
	v_mfma_f32_16x16x32_bf16 v[24:27], v[28:31], v[32:35], v[24:27]
	s_nop 7
	v_fma_f32 v16, v0, v24, v16
	v_div_scale_f32 v20, s[4:5], v4, v4, v16
	v_rcp_f32_e32 v21, v20
	v_fmac_f32_e32 v19, v3, v27
	v_fma_f32 v24, -v20, v21, 1.0
	v_fmac_f32_e32 v21, v24, v21
	v_div_scale_f32 v24, vcc, v16, v4, v16
	v_mul_f32_e32 v28, v24, v21
	v_fma_f32 v29, -v20, v28, v24
	v_fmac_f32_e32 v28, v29, v21
	v_fma_f32 v20, -v20, v28, v24
	v_div_fmas_f32 v20, v20, v21, v28
	v_div_fixup_f32 v16, v20, v4, v16
	ds_write_b32 v36, v16 offset:128
	v_fma_f32 v16, v1, v25, v17
	v_div_scale_f32 v17, s[4:5], v5, v5, v16
	v_rcp_f32_e32 v20, v17
	s_nop 0
	v_fma_f32 v21, -v17, v20, 1.0
	v_fmac_f32_e32 v20, v21, v20
	v_div_scale_f32 v21, vcc, v16, v5, v16
	v_mul_f32_e32 v24, v21, v20
	v_fma_f32 v25, -v17, v24, v21
	v_fmac_f32_e32 v24, v25, v20
	v_fma_f32 v17, -v17, v24, v21
	v_div_fmas_f32 v17, v17, v20, v24
	v_div_fixup_f32 v16, v17, v5, v16
	ds_write_b32 v23, v16 offset:128
	v_fma_f32 v16, v2, v26, v18
	v_div_scale_f32 v17, s[4:5], v6, v6, v16
	v_rcp_f32_e32 v18, v17
	s_nop 0
	v_fma_f32 v20, -v17, v18, 1.0
	v_fmac_f32_e32 v18, v20, v18
	v_div_scale_f32 v20, vcc, v16, v6, v16
	v_mul_f32_e32 v21, v20, v18
	v_fma_f32 v23, -v17, v21, v20
	v_fmac_f32_e32 v21, v23, v18
	v_fma_f32 v17, -v17, v21, v20
	v_div_fmas_f32 v17, v17, v18, v21
	v_div_fixup_f32 v16, v17, v6, v16
	ds_write_b32 v37, v16 offset:128
	v_div_scale_f32 v16, s[4:5], v7, v7, v19
	v_rcp_f32_e32 v17, v16
	s_nop 0
	v_fma_f32 v18, -v16, v17, 1.0
	v_fmac_f32_e32 v17, v18, v17
	v_div_scale_f32 v18, vcc, v19, v7, v19
	v_mul_f32_e32 v20, v18, v17
	v_fma_f32 v21, -v16, v20, v18
	v_fmac_f32_e32 v20, v21, v17
	v_fma_f32 v16, -v16, v20, v18
	v_div_fmas_f32 v16, v16, v17, v20
	v_div_fixup_f32 v16, v16, v7, v19
	ds_write_b32 v38, v16 offset:128
	ds_read_b128 v[16:19], v10 offset:59904
	ds_read_b128 v[24:27], v8 offset:18432
	s_waitcnt lgkmcnt(0)
	v_mfma_f32_16x16x32_bf16 v[16:19], v[16:19], v[24:27], 0
	ds_read_b128 v[24:27], v10 offset:59968
	ds_read_b128 v[28:31], v8 offset:18496
	s_waitcnt lgkmcnt(0)
	v_mfma_f32_16x16x32_bf16 v[16:19], v[24:27], v[28:31], v[16:19]
	ds_read_b128 v[24:27], v10
	ds_read_b128 v[28:31], v8 offset:39168
	s_waitcnt lgkmcnt(0)
	v_mfma_f32_16x16x32_bf16 v[24:27], v[24:27], v[28:31], 0
	ds_read_b128 v[28:31], v10 offset:64
	ds_read_b128 v[32:35], v8 offset:39232
	v_lshl_add_u32 v8, s2, 2, v12
	s_lshl_b32 s2, s3, 3
	s_waitcnt lgkmcnt(0)
	v_mfma_f32_16x16x32_bf16 v[24:27], v[28:31], v[32:35], v[24:27]
	s_mulk_i32 s3, 0x1080
	s_nop 6
	v_fma_f32 v0, v0, v24, v16
	v_div_scale_f32 v9, s[4:5], v4, v4, v0
	v_rcp_f32_e32 v10, v9
	v_fmac_f32_e32 v19, v3, v27
	v_fma_f32 v12, -v9, v10, 1.0
	v_fmac_f32_e32 v10, v12, v10
	v_div_scale_f32 v12, vcc, v0, v4, v0
	v_mul_f32_e32 v16, v12, v10
	v_fma_f32 v20, -v9, v16, v12
	v_fmac_f32_e32 v16, v20, v10
	v_fma_f32 v9, -v9, v16, v12
	v_div_fmas_f32 v9, v9, v10, v16
	v_div_fixup_f32 v0, v9, v4, v0
	v_mad_u32_u24 v4, v11, s6, v8
	ds_write_b32 v4, v0
	v_fma_f32 v0, v1, v25, v17
	v_div_scale_f32 v1, s[4:5], v5, v5, v0
	v_rcp_f32_e32 v4, v1
	s_nop 0
	v_fma_f32 v9, -v1, v4, 1.0
	v_fmac_f32_e32 v4, v9, v4
	v_div_scale_f32 v9, vcc, v0, v5, v0
	v_mul_f32_e32 v10, v9, v4
	v_fma_f32 v11, -v1, v10, v9
	v_fmac_f32_e32 v10, v11, v4
	v_fma_f32 v1, -v1, v10, v9
	v_div_fmas_f32 v1, v1, v4, v10
	v_div_fixup_f32 v0, v1, v5, v0
	v_add_u32_e32 v1, v8, v13
	ds_write_b32 v1, v0
	v_fma_f32 v0, v2, v26, v18
	v_div_scale_f32 v1, s[4:5], v6, v6, v0
	v_rcp_f32_e32 v2, v1
	s_nop 0
	v_fma_f32 v4, -v1, v2, 1.0
	v_fmac_f32_e32 v2, v4, v2
	v_div_scale_f32 v4, vcc, v0, v6, v0
	v_mul_f32_e32 v5, v4, v2
	v_fma_f32 v9, -v1, v5, v4
	v_fmac_f32_e32 v5, v9, v2
	v_fma_f32 v1, -v1, v5, v4
	v_div_fmas_f32 v1, v1, v2, v5
	v_div_fixup_f32 v0, v1, v6, v0
	v_add_u32_e32 v1, v8, v14
	ds_write_b32 v1, v0
	v_div_scale_f32 v0, s[4:5], v7, v7, v19
	v_rcp_f32_e32 v1, v0
	s_nop 0
	v_fma_f32 v2, -v0, v1, 1.0
	v_fmac_f32_e32 v1, v2, v1
	v_div_scale_f32 v2, vcc, v19, v7, v19
	v_mul_f32_e32 v3, v2, v1
	v_fma_f32 v4, -v0, v3, v2
	v_fmac_f32_e32 v3, v4, v1
	v_fma_f32 v0, -v0, v3, v2
	v_lshlrev_b32_e32 v2, 3, v22
	v_div_fmas_f32 v0, v0, v1, v3
	v_add_u32_e32 v10, s7, v2
	v_div_fixup_f32 v0, v0, v7, v19
	v_add_u32_e32 v1, v8, v15
	v_add_u32_e32 v6, s3, v10
	ds_write_b32 v1, v0
	s_waitcnt lgkmcnt(0)
	s_barrier
	s_add_u32 s4, s34, s2
	s_addc_u32 s5, s35, 0
	s_lshl_b64 s[4:5], s[4:5], 11
	s_lshl_b32 s3, s12, 1
	v_lshl_or_b32 v3, v22, 2, s3
	ds_read_b64 v[48:49], v6
	ds_read_b64 v[50:51], v6 offset:528
	ds_read_b64 v[52:53], v6 offset:1056
	ds_read_b64 v[54:55], v6 offset:1584
	ds_read_b64 v[56:57], v6 offset:2112
	ds_read_b64 v[58:59], v6 offset:2640
	ds_read_b64 v[60:61], v6 offset:3168
	ds_read_b64 v[62:63], v6 offset:3696
	s_add_u32 s2, s22, s4
	s_addc_u32 s3, s23, s5
	s_add_u32 s98, s24, s4
	s_addc_u32 s99, s25, s5
	global_load_dword v80, v3, s[2:3]
	global_load_dword v81, v3, s[2:3] offset:2048
	s_add_u32 s2, s2, 0x1000
	s_addc_u32 s3, s3, 0
	global_load_dword v82, v3, s[2:3]
	global_load_dword v83, v3, s[2:3] offset:2048
	s_add_u32 s2, s2, 0x1000
	s_addc_u32 s3, s3, 0
	global_load_dword v84, v3, s[2:3]
	global_load_dword v85, v3, s[2:3] offset:2048
	s_add_u32 s2, s2, 0x1000
	s_addc_u32 s3, s3, 0
	global_load_dword v86, v3, s[2:3]
	global_load_dword v87, v3, s[2:3] offset:2048
	global_load_dwordx2 v[88:89], v2, s[20:21]
	v_lshlrev_b32_e32 v90, 2, v201
	v_xor_b32_e32 v91, 4, v90
	v_xor_b32_e32 v92, 8, v90
	v_xor_b32_e32 v93, 16, v90
	v_xor_b32_e32 v94, 32, v90
	v_xor_b32_e32 v95, 64, v90
	v_xor_b32_e32 v96, 0x80, v90
	s_waitcnt lgkmcnt(0)
	v_pk_mul_f32 v[98:99], v[48:49], v[48:49]
	v_add_f32_e32 v64, v98, v99
	v_pk_mul_f32 v[98:99], v[50:51], v[50:51]
	v_add_f32_e32 v65, v98, v99
	v_pk_mul_f32 v[98:99], v[52:53], v[52:53]
	v_add_f32_e32 v66, v98, v99
	v_pk_mul_f32 v[98:99], v[54:55], v[54:55]
	v_add_f32_e32 v67, v98, v99
	v_pk_mul_f32 v[98:99], v[56:57], v[56:57]
	v_add_f32_e32 v68, v98, v99
	v_pk_mul_f32 v[98:99], v[58:59], v[58:59]
	v_add_f32_e32 v69, v98, v99
	v_pk_mul_f32 v[98:99], v[60:61], v[60:61]
	v_add_f32_e32 v70, v98, v99
	v_pk_mul_f32 v[98:99], v[62:63], v[62:63]
	v_add_f32_e32 v71, v98, v99
	ds_bpermute_b32 v72, v91, v64
	ds_bpermute_b32 v73, v91, v65
	ds_bpermute_b32 v74, v91, v66
	ds_bpermute_b32 v75, v91, v67
	ds_bpermute_b32 v76, v91, v68
	ds_bpermute_b32 v77, v91, v69
	ds_bpermute_b32 v78, v91, v70
	ds_bpermute_b32 v79, v91, v71
	s_waitcnt lgkmcnt(0)
	v_add_f32_e32 v64, v64, v72
	v_add_f32_e32 v65, v65, v73
	v_add_f32_e32 v66, v66, v74
	v_add_f32_e32 v67, v67, v75
	v_add_f32_e32 v68, v68, v76
	v_add_f32_e32 v69, v69, v77
	v_add_f32_e32 v70, v70, v78
	v_add_f32_e32 v71, v71, v79
	ds_bpermute_b32 v72, v92, v64
	ds_bpermute_b32 v73, v92, v65
	ds_bpermute_b32 v74, v92, v66
	ds_bpermute_b32 v75, v92, v67
	ds_bpermute_b32 v76, v92, v68
	ds_bpermute_b32 v77, v92, v69
	ds_bpermute_b32 v78, v92, v70
	ds_bpermute_b32 v79, v92, v71
	s_waitcnt lgkmcnt(0)
	v_add_f32_e32 v64, v64, v72
	v_add_f32_e32 v65, v65, v73
	v_add_f32_e32 v66, v66, v74
	v_add_f32_e32 v67, v67, v75
	v_add_f32_e32 v68, v68, v76
	v_add_f32_e32 v69, v69, v77
	v_add_f32_e32 v70, v70, v78
	v_add_f32_e32 v71, v71, v79
	ds_bpermute_b32 v72, v93, v64
	ds_bpermute_b32 v73, v93, v65
	ds_bpermute_b32 v74, v93, v66
	ds_bpermute_b32 v75, v93, v67
	ds_bpermute_b32 v76, v93, v68
	ds_bpermute_b32 v77, v93, v69
	ds_bpermute_b32 v78, v93, v70
	ds_bpermute_b32 v79, v93, v71
	s_waitcnt lgkmcnt(0)
	v_add_f32_e32 v64, v64, v72
	v_add_f32_e32 v65, v65, v73
	v_add_f32_e32 v66, v66, v74
	v_add_f32_e32 v67, v67, v75
	v_add_f32_e32 v68, v68, v76
	v_add_f32_e32 v69, v69, v77
	v_add_f32_e32 v70, v70, v78
	v_add_f32_e32 v71, v71, v79
	ds_bpermute_b32 v72, v94, v64
	ds_bpermute_b32 v73, v94, v65
	ds_bpermute_b32 v74, v94, v66
	ds_bpermute_b32 v75, v94, v67
	ds_bpermute_b32 v76, v94, v68
	ds_bpermute_b32 v77, v94, v69
	ds_bpermute_b32 v78, v94, v70
	ds_bpermute_b32 v79, v94, v71
	s_waitcnt lgkmcnt(0)
	v_add_f32_e32 v64, v64, v72
	v_add_f32_e32 v65, v65, v73
	v_add_f32_e32 v66, v66, v74
	v_add_f32_e32 v67, v67, v75
	v_add_f32_e32 v68, v68, v76
	v_add_f32_e32 v69, v69, v77
	v_add_f32_e32 v70, v70, v78
	v_add_f32_e32 v71, v71, v79
	ds_bpermute_b32 v72, v95, v64
	ds_bpermute_b32 v73, v95, v65
	ds_bpermute_b32 v74, v95, v66
	ds_bpermute_b32 v75, v95, v67
	ds_bpermute_b32 v76, v95, v68
	ds_bpermute_b32 v77, v95, v69
	ds_bpermute_b32 v78, v95, v70
	ds_bpermute_b32 v79, v95, v71
	s_waitcnt lgkmcnt(0)
	v_add_f32_e32 v64, v64, v72
	v_add_f32_e32 v65, v65, v73
	v_add_f32_e32 v66, v66, v74
	v_add_f32_e32 v67, v67, v75
	v_add_f32_e32 v68, v68, v76
	v_add_f32_e32 v69, v69, v77
	v_add_f32_e32 v70, v70, v78
	v_add_f32_e32 v71, v71, v79
	ds_bpermute_b32 v72, v96, v64
	ds_bpermute_b32 v73, v96, v65
	ds_bpermute_b32 v74, v96, v66
	ds_bpermute_b32 v75, v96, v67
	ds_bpermute_b32 v76, v96, v68
	ds_bpermute_b32 v77, v96, v69
	ds_bpermute_b32 v78, v96, v70
	ds_bpermute_b32 v79, v96, v71
	s_waitcnt lgkmcnt(0)
	v_add_f32_e32 v64, v64, v72
	v_add_f32_e32 v65, v65, v73
	v_add_f32_e32 v66, v66, v74
	v_add_f32_e32 v67, v67, v75
	v_add_f32_e32 v68, v68, v76
	v_add_f32_e32 v69, v69, v77
	v_add_f32_e32 v70, v70, v78
	v_add_f32_e32 v71, v71, v79
	v_fmamk_f32 v64, v64, 0x3c000000, v195
	v_cmp_gt_f32_e32 vcc, s67, v64
	v_mul_f32_e32 v72, 0x4b800000, v64
	s_nop 0
	v_cndmask_b32_e32 v64, v64, v72, vcc
	v_rsq_f32_e32 v64, v64
	s_nop 0
	v_mul_f32_e32 v72, 0x45800000, v64
	v_cndmask_b32_e32 v64, v64, v72, vcc
	v_fmamk_f32 v65, v65, 0x3c000000, v195
	v_cmp_gt_f32_e32 vcc, s67, v65
	v_mul_f32_e32 v73, 0x4b800000, v65
	s_nop 0
	v_cndmask_b32_e32 v65, v65, v73, vcc
	v_rsq_f32_e32 v65, v65
	s_nop 0
	v_mul_f32_e32 v73, 0x45800000, v65
	v_cndmask_b32_e32 v65, v65, v73, vcc
	v_fmamk_f32 v66, v66, 0x3c000000, v195
	v_cmp_gt_f32_e32 vcc, s67, v66
	v_mul_f32_e32 v74, 0x4b800000, v66
	s_nop 0
	v_cndmask_b32_e32 v66, v66, v74, vcc
	v_rsq_f32_e32 v66, v66
	s_nop 0
	v_mul_f32_e32 v74, 0x45800000, v66
	v_cndmask_b32_e32 v66, v66, v74, vcc
	v_fmamk_f32 v67, v67, 0x3c000000, v195
	v_cmp_gt_f32_e32 vcc, s67, v67
	v_mul_f32_e32 v75, 0x4b800000, v67
	s_nop 0
	v_cndmask_b32_e32 v67, v67, v75, vcc
	v_rsq_f32_e32 v67, v67
	s_nop 0
	v_mul_f32_e32 v75, 0x45800000, v67
	v_cndmask_b32_e32 v67, v67, v75, vcc
	v_fmamk_f32 v68, v68, 0x3c000000, v195
	v_cmp_gt_f32_e32 vcc, s67, v68
	v_mul_f32_e32 v76, 0x4b800000, v68
	s_nop 0
	v_cndmask_b32_e32 v68, v68, v76, vcc
	v_rsq_f32_e32 v68, v68
	s_nop 0
	v_mul_f32_e32 v76, 0x45800000, v68
	v_cndmask_b32_e32 v68, v68, v76, vcc
	v_fmamk_f32 v69, v69, 0x3c000000, v195
	v_cmp_gt_f32_e32 vcc, s67, v69
	v_mul_f32_e32 v77, 0x4b800000, v69
	s_nop 0
	v_cndmask_b32_e32 v69, v69, v77, vcc
	v_rsq_f32_e32 v69, v69
	s_nop 0
	v_mul_f32_e32 v77, 0x45800000, v69
	v_cndmask_b32_e32 v69, v69, v77, vcc
	v_fmamk_f32 v70, v70, 0x3c000000, v195
	v_cmp_gt_f32_e32 vcc, s67, v70
	v_mul_f32_e32 v78, 0x4b800000, v70
	s_nop 0
	v_cndmask_b32_e32 v70, v70, v78, vcc
	v_rsq_f32_e32 v70, v70
	s_nop 0
	v_mul_f32_e32 v78, 0x45800000, v70
	v_cndmask_b32_e32 v70, v70, v78, vcc
	v_fmamk_f32 v71, v71, 0x3c000000, v195
	v_cmp_gt_f32_e32 vcc, s67, v71
	v_mul_f32_e32 v79, 0x4b800000, v71
	s_nop 0
	v_cndmask_b32_e32 v71, v71, v79, vcc
	v_rsq_f32_e32 v71, v71
	s_nop 0
	v_mul_f32_e32 v79, 0x45800000, v71
	v_cndmask_b32_e32 v71, v71, v79, vcc
	s_waitcnt vmcnt(0)
	v_mul_f32_e32 v48, v48, v64
	v_mul_f32_e32 v49, v49, v64
	v_pk_mul_f32 v[48:49], v[88:89], v[48:49]
	v_lshlrev_b32_e32 v72, 16, v80
	v_and_b32_e32 v80, 0xffff0000, v80
	v_mul_f32_e32 v48, v48, v72
	v_mul_f32_e32 v49, v49, v80
	v_cvt_pk_bf16_f32 v72, v48, v49
	global_store_dword v3, v72, s[98:99]
	v_mul_f32_e32 v50, v50, v65
	v_mul_f32_e32 v51, v51, v65
	v_pk_mul_f32 v[50:51], v[88:89], v[50:51]
	v_lshlrev_b32_e32 v73, 16, v81
	v_and_b32_e32 v81, 0xffff0000, v81
	v_mul_f32_e32 v50, v50, v73
	v_mul_f32_e32 v51, v51, v81
	v_cvt_pk_bf16_f32 v73, v50, v51
	global_store_dword v3, v73, s[98:99] offset:2048
	s_add_u32 s98, s98, 0x1000
	s_addc_u32 s99, s99, 0
	v_mul_f32_e32 v52, v52, v66
	v_mul_f32_e32 v53, v53, v66
	v_pk_mul_f32 v[52:53], v[88:89], v[52:53]
	v_lshlrev_b32_e32 v74, 16, v82
	v_and_b32_e32 v82, 0xffff0000, v82
	v_mul_f32_e32 v52, v52, v74
	v_mul_f32_e32 v53, v53, v82
	v_cvt_pk_bf16_f32 v74, v52, v53
	global_store_dword v3, v74, s[98:99]
	v_mul_f32_e32 v54, v54, v67
	v_mul_f32_e32 v55, v55, v67
	v_pk_mul_f32 v[54:55], v[88:89], v[54:55]
	v_lshlrev_b32_e32 v75, 16, v83
	v_and_b32_e32 v83, 0xffff0000, v83
	v_mul_f32_e32 v54, v54, v75
	v_mul_f32_e32 v55, v55, v83
	v_cvt_pk_bf16_f32 v75, v54, v55
	global_store_dword v3, v75, s[98:99] offset:2048
	s_add_u32 s98, s98, 0x1000
	s_addc_u32 s99, s99, 0
	v_mul_f32_e32 v56, v56, v68
	v_mul_f32_e32 v57, v57, v68
	v_pk_mul_f32 v[56:57], v[88:89], v[56:57]
	v_lshlrev_b32_e32 v76, 16, v84
	v_and_b32_e32 v84, 0xffff0000, v84
	v_mul_f32_e32 v56, v56, v76
	v_mul_f32_e32 v57, v57, v84
	v_cvt_pk_bf16_f32 v76, v56, v57
	global_store_dword v3, v76, s[98:99]
	v_mul_f32_e32 v58, v58, v69
	v_mul_f32_e32 v59, v59, v69
	v_pk_mul_f32 v[58:59], v[88:89], v[58:59]
	v_lshlrev_b32_e32 v77, 16, v85
	v_and_b32_e32 v85, 0xffff0000, v85
	v_mul_f32_e32 v58, v58, v77
	v_mul_f32_e32 v59, v59, v85
	v_cvt_pk_bf16_f32 v77, v58, v59
	global_store_dword v3, v77, s[98:99] offset:2048
	s_add_u32 s98, s98, 0x1000
	s_addc_u32 s99, s99, 0
	v_mul_f32_e32 v60, v60, v70
	v_mul_f32_e32 v61, v61, v70
	v_pk_mul_f32 v[60:61], v[88:89], v[60:61]
	v_lshlrev_b32_e32 v78, 16, v86
	v_and_b32_e32 v86, 0xffff0000, v86
	v_mul_f32_e32 v60, v60, v78
	v_mul_f32_e32 v61, v61, v86
	v_cvt_pk_bf16_f32 v78, v60, v61
	global_store_dword v3, v78, s[98:99]
	v_mul_f32_e32 v62, v62, v71
	v_mul_f32_e32 v63, v63, v71
	v_pk_mul_f32 v[62:63], v[88:89], v[62:63]
	v_lshlrev_b32_e32 v79, 16, v87
	v_and_b32_e32 v87, 0xffff0000, v87
	v_mul_f32_e32 v62, v62, v79
	v_mul_f32_e32 v63, v63, v87
	v_cvt_pk_bf16_f32 v79, v62, v63
	global_store_dword v3, v79, s[98:99] offset:2048
	s_add_i32 s39, s39, s71
	s_cmpk_gt_i32 s39, 0x7ff
	s_barrier
	s_cbranch_scc1 .LBB0_494

	.amdhsa_kernel _Z10hybrid_fwd6Params
		.amdhsa_group_segment_fixed_size 0
		.amdhsa_private_segment_fixed_size 0
		.amdhsa_kernarg_size 544
		.amdhsa_user_sgpr_count 2
		.amdhsa_user_sgpr_dispatch_ptr 0
		.amdhsa_user_sgpr_queue_ptr 0
		.amdhsa_user_sgpr_kernarg_segment_ptr 1
		.amdhsa_user_sgpr_dispatch_id 0
		.amdhsa_user_sgpr_kernarg_preload_length 0
		.amdhsa_user_sgpr_kernarg_preload_offset 0
		.amdhsa_user_sgpr_private_segment_size 0
		.amdhsa_uses_dynamic_stack 0
		.amdhsa_enable_private_segment 0
		.amdhsa_system_sgpr_workgroup_id_x 1
		.amdhsa_system_sgpr_workgroup_id_y 0
		.amdhsa_system_sgpr_workgroup_id_z 0
		.amdhsa_system_sgpr_workgroup_info 0
		.amdhsa_system_vgpr_workitem_id 2
		.amdhsa_next_free_vgpr 256
		.amdhsa_next_free_sgpr 102
		.amdhsa_accum_offset 256
		.amdhsa_reserve_vcc 1
		.amdhsa_float_round_mode_32 0
		.amdhsa_float_round_mode_16_64 0
		.amdhsa_float_denorm_mode_32 3
		.amdhsa_float_denorm_mode_16_64 3
		.amdhsa_dx10_clamp 1
		.amdhsa_ieee_mode 1
		.amdhsa_fp16_overflow 0
		.amdhsa_tg_split 0
		.amdhsa_exception_fp_ieee_invalid_op 0
		.amdhsa_exception_fp_denorm_src 0
		.amdhsa_exception_fp_ieee_div_zero 0
		.amdhsa_exception_fp_ieee_overflow 0
		.amdhsa_exception_fp_ieee_underflow 0
		.amdhsa_exception_fp_ieee_inexact 0
		.amdhsa_exception_int_div_zero 0
	.end_amdhsa_kernel

amdhsa.kernels:
  - .agpr_count:     0
    .args:
      - .offset:         0
        .size:           288
        .value_kind:     by_value
      - .offset:         288
        .size:           4
        .value_kind:     hidden_block_count_x
      - .offset:         292
        .size:           4
        .value_kind:     hidden_block_count_y
      - .offset:         296
        .size:           4
        .value_kind:     hidden_block_count_z
      - .offset:         300
        .size:           2
        .value_kind:     hidden_group_size_x
      - .offset:         302
        .size:           2
        .value_kind:     hidden_group_size_y
      - .offset:         304
        .size:           2
        .value_kind:     hidden_group_size_z
      - .offset:         306
        .size:           2
        .value_kind:     hidden_remainder_x
      - .offset:         308
        .size:           2
        .value_kind:     hidden_remainder_y
      - .offset:         310
        .size:           2
        .value_kind:     hidden_remainder_z
      - .offset:         328
        .size:           8
        .value_kind:     hidden_global_offset_x
      - .offset:         336
        .size:           8
        .value_kind:     hidden_global_offset_y
      - .offset:         344
        .size:           8
        .value_kind:     hidden_global_offset_z
      - .offset:         352
        .size:           2
        .value_kind:     hidden_grid_dims
      - .offset:         376
        .size:           8
        .value_kind:     hidden_multigrid_sync_arg
      - .offset:         408
        .size:           4
        .value_kind:     hidden_dynamic_lds_size
    .group_segment_fixed_size: 0
    .kernarg_segment_align: 8
    .kernarg_segment_size: 544
    .language:       OpenCL C
    .language_version:
      - 2
      - 0
    .max_flat_workgroup_size: 512
    .name:           _Z10hybrid_fwd6Params
    .private_segment_fixed_size: 0
    .sgpr_count:     108
    .sgpr_spill_count: 122
    .symbol:         _Z10hybrid_fwd6Params.kd
    .uniform_work_group_size: 1
    .uses_dynamic_stack: false
    .vgpr_count:     256
    .vgpr_spill_count: 0
    .wavefront_size: 64
